# attention tile loop: typical path falls through (rare rescale and vmcnt(0) variant out of line), merged back edge, next-tile LDS addresses computed before the barrier
# speedup vs baseline: 1.0008x; 1.0008x over previous
.LBB0_55:
	v_sub_u32_e64 v1, s40, v232 clamp
	s_min_u32 s30, s40, 0xe80
	s_addk_i32 s30, 0x180
	v_readfirstlane_b32 s31, v1
	s_lshr_b32 s35, s31, 6
	s_lshr_b32 s36, s30, 6
	s_and_b64 s[30:31], s[28:29], exec
	s_cselect_b32 s30, s41, s36
	s_cselect_b32 s40, 0, s35
	s_waitcnt vmcnt(0) lgkmcnt(0)
	s_barrier
	v_mov_b32_e32 v30, v0
	s_sub_i32 s41, s30, s40
	v_mov_b32_e32 v29, v0
	v_mov_b32_e32 v28, v0
	v_mov_b32_e32 v27, v0
	v_mov_b32_e32 v26, v0
	v_mov_b32_e32 v25, v0
	v_mov_b32_e32 v24, v0
	v_mov_b32_e32 v23, v0
	v_mov_b32_e32 v22, v0
	v_mov_b32_e32 v21, v0
	v_mov_b32_e32 v20, v0
	v_mov_b32_e32 v19, v0
	v_mov_b32_e32 v18, v0
	v_mov_b32_e32 v17, v0
	v_mov_b32_e32 v16, v0
	v_mov_b32_e32 v15, v0
	v_mov_b32_e32 v14, v0
	v_mov_b32_e32 v13, v0
	v_mov_b32_e32 v12, v0
	v_mov_b32_e32 v11, v0
	v_mov_b32_e32 v10, v0
	v_mov_b32_e32 v9, v0
	v_mov_b32_e32 v8, v0
	v_mov_b32_e32 v7, v0
	v_mov_b32_e32 v6, v0
	v_mov_b32_e32 v5, v0
	v_mov_b32_e32 v4, v0
	v_mov_b32_e32 v3, v0
	v_mov_b32_e32 v2, v0
	v_mov_b32_e32 v1, v0
	v_mov_b64_e32 v[62:63], v[30:31]
	s_cmp_gt_i32 s41, -4
	v_mov_b32_e32 v121, v113
	v_mov_b64_e32 v[32:33], v[0:1]
	v_mov_b64_e32 v[60:61], v[28:29]
	v_mov_b64_e32 v[58:59], v[26:27]
	v_mov_b64_e32 v[56:57], v[24:25]
	v_mov_b64_e32 v[54:55], v[22:23]
	v_mov_b64_e32 v[52:53], v[20:21]
	v_mov_b64_e32 v[50:51], v[18:19]
	v_mov_b64_e32 v[48:49], v[16:17]
	v_mov_b64_e32 v[46:47], v[14:15]
	v_mov_b64_e32 v[44:45], v[12:13]
	v_mov_b64_e32 v[42:43], v[10:11]
	v_mov_b64_e32 v[40:41], v[8:9]
	v_mov_b64_e32 v[38:39], v[6:7]
	v_mov_b64_e32 v[36:37], v[4:5]
	v_mov_b64_e32 v[34:35], v[2:3]
	s_cbranch_scc0 .LBB0_38
	s_lshl_b32 s42, s42, 12
	s_lshl_b32 s30, s43, 8
	s_add_i32 s41, s41, 4
	s_addk_i32 s42, 0xff00
	s_sub_i32 s30, 0, s30
	s_and_b64 s[28:29], s[28:29], exec
	s_cselect_b32 s28, 0xfffff000, s30
	s_lshl_b32 s29, s44, 7
	v_add_u32_e32 v123, s29, v112
	v_add_u32_e32 v125, s29, v114
	s_lshl_b32 s29, s40, 6
	s_add_i32 s29, s29, s28
	v_mov_b32_e32 v1, v0
	v_mov_b32_e32 v2, v0
	v_mov_b32_e32 v3, v0
	v_mov_b32_e32 v4, v0
	v_mov_b32_e32 v5, v0
	v_mov_b32_e32 v6, v0
	v_mov_b32_e32 v7, v0
	v_mov_b32_e32 v8, v0
	v_mov_b32_e32 v9, v0
	v_mov_b32_e32 v10, v0
	v_mov_b32_e32 v11, v0
	v_mov_b32_e32 v12, v0
	v_mov_b32_e32 v13, v0
	v_mov_b32_e32 v14, v0
	v_mov_b32_e32 v15, v0
	v_mov_b32_e32 v16, v0
	v_mov_b32_e32 v17, v0
	v_mov_b32_e32 v18, v0
	v_mov_b32_e32 v19, v0
	v_mov_b32_e32 v20, v0
	v_mov_b32_e32 v21, v0
	v_mov_b32_e32 v22, v0
	v_mov_b32_e32 v23, v0
	v_mov_b32_e32 v24, v0
	v_mov_b32_e32 v25, v0
	v_mov_b32_e32 v26, v0
	v_mov_b32_e32 v27, v0
	v_mov_b32_e32 v28, v0
	v_mov_b32_e32 v29, v0
	v_mov_b32_e32 v30, v0
	v_mov_b32_e32 v31, v0
	s_waitcnt vmcnt(0)
	v_mul_f32_e32 v131, 0x3fb8aa3b, v64
	v_sub_f32_e32 v154, 0, v131
	v_mov_b32_e32 v155, v154
	v_mov_b32_e32 v156, v154
	v_mov_b32_e32 v157, v154
	v_mov_b32_e32 v158, v154
	v_mov_b32_e32 v159, v154
	v_mov_b32_e32 v160, v154
	v_mov_b32_e32 v161, v154
	v_mov_b32_e32 v162, v154
	v_mov_b32_e32 v163, v154
	v_mov_b32_e32 v164, v154
	v_mov_b32_e32 v165, v154
	v_mov_b32_e32 v166, v154
	v_mov_b32_e32 v167, v154
	v_mov_b32_e32 v168, v154
	v_mov_b32_e32 v169, v154
	s_mov_b32 s43, 0
	v_add_u32_e32 v127, s29, v134
	s_add_i32 s44, s34, 0x80
	s_mov_b32 s45, 2
	s_mov_b32 s46, 1
	v_mov_b32_e32 v121, v113
	s_mov_b32 s48, 0
	s_mov_b32 s47, 0
	s_mul_i32 s34, s48, 0x2400
	v_add_u32_e32 v208, s34, v115
	s_mul_i32 s34, s48, 0x2400
	v_add_u32_e32 v209, s34, v133
	v_readfirstlane_b32 s30, v191
	s_lshr_b32 s30, s30, 8
	s_cmp_eq_u32 s30, 0
	s_cbranch_scc1 .Latt_swa_p0
	s_setprio 1

.Latt_swa_nomasktest:
	ds_read_b128 v[210:213], v208 offset:0
	ds_read_b128 v[214:217], v208 offset:4608
	ds_read_b128 v[218:221], v208 offset:32
	ds_read_b128 v[222:225], v208 offset:4640
	ds_read_b128 v[226:229], v208 offset:64
	ds_read_b128 v[238:241], v208 offset:4672
	ds_read_b128 v[242:245], v208 offset:96
	ds_read_b128 v[246:249], v208 offset:4704
	s_waitcnt lgkmcnt(7)
	v_mfma_f32_32x32x16_bf16 v[64:79], v[210:213], v[96:99], v[154:169]
	s_waitcnt lgkmcnt(6)
	v_mfma_f32_32x32x16_bf16 v[32:47], v[214:217], v[96:99], v[154:169]
	s_waitcnt lgkmcnt(5)
	v_mfma_f32_32x32x16_bf16 v[64:79], v[218:221], v[100:103], v[64:79]
	s_waitcnt lgkmcnt(4)
	v_mfma_f32_32x32x16_bf16 v[32:47], v[222:225], v[100:103], v[32:47]
	s_waitcnt lgkmcnt(3)
	v_mfma_f32_32x32x16_bf16 v[64:79], v[226:229], v[104:107], v[64:79]
	s_waitcnt lgkmcnt(2)
	v_mfma_f32_32x32x16_bf16 v[32:47], v[238:241], v[104:107], v[32:47]
	s_waitcnt lgkmcnt(1)
	v_mfma_f32_32x32x16_bf16 v[64:79], v[242:245], v[108:111], v[64:79]
	s_waitcnt lgkmcnt(0)
	v_mfma_f32_32x32x16_bf16 v[32:47], v[246:249], v[108:111], v[32:47]
	ds_read_b128 v[210:213], v209 offset:27648
	ds_read_b128 v[214:217], v209 offset:32256
	ds_read_b128 v[218:221], v209 offset:27680
	ds_read_b128 v[222:225], v209 offset:32288
	ds_read_b128 v[226:229], v209 offset:27712
	ds_read_b128 v[238:241], v209 offset:32320
	ds_read_b128 v[242:245], v209 offset:27744
	ds_read_b128 v[246:249], v209 offset:32352
	s_nop 2
	s_nop 0
	s_cmp_lt_u32 s47, 4
	s_cbranch_scc1 .Latt_swa_nomask
	s_cmp_eq_u64 s[36:37], exec
	s_cbranch_scc1 .Latt_swa_nomask
	v_add_u32_e32 v48, s43, v127
	v_add_u32_e32 v49, 0xfffffe7f, v48
	v_cmp_lt_u32_e32 vcc, s50, v49
	v_add_u32_e32 v49, 0xfffffe9f, v48
	s_nop 0
	v_cndmask_b32_e32 v64, v233, v64, vcc
	v_cmp_lt_u32_e32 vcc, s50, v49
	v_add_u32_e32 v49, 0xfffffe80, v48
	s_nop 0
	v_cndmask_b32_e32 v32, v233, v32, vcc
	v_cmp_lt_u32_e32 vcc, s50, v49
	v_add_u32_e32 v49, 0xfffffea0, v48
	s_nop 0
	v_cndmask_b32_e32 v65, v233, v65, vcc
	v_cmp_lt_u32_e32 vcc, s50, v49
	v_add_u32_e32 v49, 0xfffffe81, v48
	s_nop 0
	v_cndmask_b32_e32 v33, v233, v33, vcc
	v_cmp_lt_u32_e32 vcc, s50, v49
	v_add_u32_e32 v49, 0xfffffea1, v48
	s_nop 0
	v_cndmask_b32_e32 v66, v233, v66, vcc
	v_cmp_lt_u32_e32 vcc, s50, v49
	v_add_u32_e32 v49, 0xfffffe82, v48
	s_nop 0
	v_cndmask_b32_e32 v34, v233, v34, vcc
	v_cmp_lt_u32_e32 vcc, s50, v49
	v_add_u32_e32 v49, 0xfffffea2, v48
	s_nop 0
	v_cndmask_b32_e32 v67, v233, v67, vcc
	v_cmp_lt_u32_e32 vcc, s50, v49
	v_add_u32_e32 v49, 0xfffffe83, v48
	s_nop 0
	v_cndmask_b32_e32 v35, v233, v35, vcc
	v_cmp_lt_u32_e32 vcc, s50, v49
	v_add_u32_e32 v49, 0xfffffea3, v48
	s_nop 0
	v_cndmask_b32_e32 v68, v233, v68, vcc
	v_cmp_lt_u32_e32 vcc, s50, v49
	v_add_u32_e32 v49, 0xfffffe84, v48
	s_nop 0
	v_cndmask_b32_e32 v36, v233, v36, vcc
	v_cmp_lt_u32_e32 vcc, s50, v49
	v_add_u32_e32 v49, 0xfffffea4, v48
	s_nop 0
	v_cndmask_b32_e32 v69, v233, v69, vcc
	v_cmp_lt_u32_e32 vcc, s50, v49
	v_add_u32_e32 v49, 0xfffffe85, v48
	s_nop 0
	v_cndmask_b32_e32 v37, v233, v37, vcc
	v_cmp_lt_u32_e32 vcc, s50, v49
	v_add_u32_e32 v49, 0xfffffea5, v48
	s_nop 0
	v_cndmask_b32_e32 v70, v233, v70, vcc
	v_cmp_lt_u32_e32 vcc, s50, v49
	v_add_u32_e32 v49, 0xfffffe86, v48
	s_nop 0
	v_cndmask_b32_e32 v38, v233, v38, vcc
	v_cmp_lt_u32_e32 vcc, s50, v49
	v_add_u32_e32 v49, 0xfffffea6, v48
	s_nop 0
	v_cndmask_b32_e32 v71, v233, v71, vcc
	v_cmp_lt_u32_e32 vcc, s50, v49
	v_add_u32_e32 v49, 0xfffffe8f, v48
	s_nop 0
	v_cndmask_b32_e32 v39, v233, v39, vcc
	v_cmp_lt_u32_e32 vcc, s50, v49
	v_add_u32_e32 v49, 0xfffffeaf, v48
	s_nop 0
	v_cndmask_b32_e32 v72, v233, v72, vcc
	v_cmp_lt_u32_e32 vcc, s50, v49
	v_add_u32_e32 v49, 0xfffffe90, v48
	s_nop 0
	v_cndmask_b32_e32 v40, v233, v40, vcc
	v_cmp_lt_u32_e32 vcc, s50, v49
	v_add_u32_e32 v49, 0xfffffeb0, v48
	s_nop 0
	v_cndmask_b32_e32 v73, v233, v73, vcc
	v_cmp_lt_u32_e32 vcc, s50, v49
	v_add_u32_e32 v49, 0xfffffe91, v48
	s_nop 0
	v_cndmask_b32_e32 v41, v233, v41, vcc
	v_cmp_lt_u32_e32 vcc, s50, v49
	v_add_u32_e32 v49, 0xfffffeb1, v48
	s_nop 0
	v_cndmask_b32_e32 v74, v233, v74, vcc
	v_cmp_lt_u32_e32 vcc, s50, v49
	v_add_u32_e32 v49, 0xfffffe92, v48
	s_nop 0
	v_cndmask_b32_e32 v42, v233, v42, vcc
	v_cmp_lt_u32_e32 vcc, s50, v49
	v_add_u32_e32 v49, 0xfffffeb2, v48
	s_nop 0
	v_cndmask_b32_e32 v75, v233, v75, vcc
	v_cmp_lt_u32_e32 vcc, s50, v49
	v_add_u32_e32 v49, 0xfffffe93, v48
	s_nop 0
	v_cndmask_b32_e32 v43, v233, v43, vcc
	v_cmp_lt_u32_e32 vcc, s50, v49
	v_add_u32_e32 v49, 0xfffffeb3, v48
	s_nop 0
	v_cndmask_b32_e32 v76, v233, v76, vcc
	v_cmp_lt_u32_e32 vcc, s50, v49
	v_add_u32_e32 v49, 0xfffffe94, v48
	s_nop 0
	v_cndmask_b32_e32 v44, v233, v44, vcc
	v_cmp_lt_u32_e32 vcc, s50, v49
	v_add_u32_e32 v49, 0xfffffeb4, v48
	s_nop 0
	v_cndmask_b32_e32 v77, v233, v77, vcc
	v_cmp_lt_u32_e32 vcc, s50, v49
	v_add_u32_e32 v49, 0xfffffe95, v48
	s_nop 0
	v_cndmask_b32_e32 v45, v233, v45, vcc
	v_cmp_lt_u32_e32 vcc, s50, v49
	v_add_u32_e32 v49, 0xfffffeb5, v48
	s_nop 0
	v_cndmask_b32_e32 v78, v233, v78, vcc
	v_cmp_lt_u32_e32 vcc, s50, v49
	v_add_u32_e32 v49, 0xfffffe96, v48
	v_add_u32_e32 v48, 0xfffffeb6, v48
	v_cndmask_b32_e32 v46, v233, v46, vcc
	v_cmp_lt_u32_e32 vcc, s50, v49
	s_nop 1
	v_cndmask_b32_e32 v79, v233, v79, vcc
	v_cmp_lt_u32_e32 vcc, s50, v48
	s_nop 1
	v_cndmask_b32_e32 v47, v233, v47, vcc
.Latt_swa_nomask:
	v_max3_f32 v198, v64, v65, v66
	v_max3_f32 v199, v67, v68, v69
	v_max3_f32 v198, v198, v70, v71
	v_max3_f32 v199, v199, v72, v73
	v_max3_f32 v198, v198, v74, v75
	v_max3_f32 v199, v199, v76, v77
	v_max3_f32 v198, v198, v78, v79
	v_max3_f32 v200, v32, v33, v34
	v_max3_f32 v201, v35, v36, v37
	v_max3_f32 v200, v200, v38, v39
	v_max3_f32 v201, v201, v40, v41
	v_max3_f32 v200, v200, v42, v43
	v_max3_f32 v201, v201, v44, v45
	v_max3_f32 v200, v200, v46, v47
	v_max3_f32 v198, v198, v199, v200
	v_max_f32_e32 v198, v198, v201
	v_cmp_lt_f32_e32 vcc, s58, v198
	s_cbranch_vccnz .Latt_swa_rare

.Latt_swa_skip:
	s_and_b64 vcc, exec, s[28:29]
	s_cbranch_vccnz .Latt_swa_w0
	s_waitcnt vmcnt(2)
.Latt_swa_wd:
	s_add_i32 s28, s45, 1
	s_cmp_lg_u32 s45, 2
	s_cselect_b32 s28, s28, 0
	s_add_i32 s47, s47, 1
	s_add_i32 s43, s43, 64
	s_mov_b32 s48, s46
	s_mov_b32 s46, s45
	s_mov_b32 s45, s28
	s_mul_i32 s34, s48, 0x2400
	v_add_u32_e32 v208, s34, v115
	s_mul_i32 s34, s48, 0x2400
	v_add_u32_e32 v209, s34, v133
	s_cmp_ge_i32 s47, s41
	s_waitcnt lgkmcnt(0)
	s_barrier
	s_cbranch_scc0 .LBB0_57
	s_branch .LBB0_37
.Latt_swa_w0:
	s_waitcnt vmcnt(0)
	s_branch .Latt_swa_wd
.Latt_swa_rare:
	v_mov_b32_e32 v199, v198
	s_nop 1
	v_permlane32_swap_b32_e32 v198, v199
	v_max_f32_e32 v202, v198, v199
	v_max_f32_e32 v203, 0, v202
	v_max_f32_e32 v204, 0, v203
	v_add_f32_e32 v131, v131, v203
	v_exp_f32_e64 v206, -v204
	v_sub_f32_e32 v154, v154, v203
	v_mov_b32_e32 v155, v154
	v_mov_b32_e32 v156, v154
	v_mov_b32_e32 v157, v154
	v_mov_b32_e32 v158, v154
	v_mov_b32_e32 v159, v154
	v_mov_b32_e32 v160, v154
	v_mov_b32_e32 v161, v154
	v_mov_b32_e32 v162, v154
	v_mov_b32_e32 v163, v154
	v_mov_b32_e32 v164, v154
	v_mov_b32_e32 v165, v154
	v_mov_b32_e32 v166, v154
	v_mov_b32_e32 v167, v154
	v_mov_b32_e32 v168, v154
	v_mov_b32_e32 v169, v154
	v_sub_f32_e32 v64, v64, v203
	v_sub_f32_e32 v65, v65, v203
	v_sub_f32_e32 v66, v66, v203
	v_sub_f32_e32 v67, v67, v203
	v_sub_f32_e32 v68, v68, v203
	v_sub_f32_e32 v69, v69, v203
	v_sub_f32_e32 v70, v70, v203
	v_sub_f32_e32 v71, v71, v203
	v_sub_f32_e32 v72, v72, v203
	v_sub_f32_e32 v73, v73, v203
	v_sub_f32_e32 v74, v74, v203
	v_sub_f32_e32 v75, v75, v203
	v_sub_f32_e32 v76, v76, v203
	v_sub_f32_e32 v77, v77, v203
	v_sub_f32_e32 v78, v78, v203
	v_sub_f32_e32 v79, v79, v203
	v_sub_f32_e32 v32, v32, v203
	v_sub_f32_e32 v33, v33, v203
	v_sub_f32_e32 v34, v34, v203
	v_sub_f32_e32 v35, v35, v203
	v_sub_f32_e32 v36, v36, v203
	v_sub_f32_e32 v37, v37, v203
	v_sub_f32_e32 v38, v38, v203
	v_sub_f32_e32 v39, v39, v203
	v_sub_f32_e32 v40, v40, v203
	v_sub_f32_e32 v41, v41, v203
	v_sub_f32_e32 v42, v42, v203
	v_sub_f32_e32 v43, v43, v203
	v_sub_f32_e32 v44, v44, v203
	v_sub_f32_e32 v45, v45, v203
	v_sub_f32_e32 v46, v46, v203
	v_sub_f32_e32 v47, v47, v203
	v_mul_f32_e32 v121, v121, v206
	v_pk_mul_f32 v[0:1], v[0:1], v[206:207] op_sel_hi:[1,0]
	v_pk_mul_f32 v[2:3], v[2:3], v[206:207] op_sel_hi:[1,0]
	v_pk_mul_f32 v[4:5], v[4:5], v[206:207] op_sel_hi:[1,0]
	v_pk_mul_f32 v[6:7], v[6:7], v[206:207] op_sel_hi:[1,0]
	v_pk_mul_f32 v[8:9], v[8:9], v[206:207] op_sel_hi:[1,0]
	v_pk_mul_f32 v[10:11], v[10:11], v[206:207] op_sel_hi:[1,0]
	v_pk_mul_f32 v[12:13], v[12:13], v[206:207] op_sel_hi:[1,0]
	v_pk_mul_f32 v[14:15], v[14:15], v[206:207] op_sel_hi:[1,0]
	v_pk_mul_f32 v[16:17], v[16:17], v[206:207] op_sel_hi:[1,0]
	v_pk_mul_f32 v[18:19], v[18:19], v[206:207] op_sel_hi:[1,0]
	v_pk_mul_f32 v[20:21], v[20:21], v[206:207] op_sel_hi:[1,0]
	v_pk_mul_f32 v[22:23], v[22:23], v[206:207] op_sel_hi:[1,0]
	v_pk_mul_f32 v[24:25], v[24:25], v[206:207] op_sel_hi:[1,0]
	v_pk_mul_f32 v[26:27], v[26:27], v[206:207] op_sel_hi:[1,0]
	v_pk_mul_f32 v[28:29], v[28:29], v[206:207] op_sel_hi:[1,0]
	v_pk_mul_f32 v[30:31], v[30:31], v[206:207] op_sel_hi:[1,0]
	s_branch .Latt_swa_norescale

.LBB0_106:
	v_mov_b32_e32 v14, v0
	v_mov_b32_e32 v15, v0
	s_waitcnt vmcnt(0) lgkmcnt(0)
	s_barrier
	v_mov_b32_e32 v1, v0
	v_mov_b32_e32 v2, v0
	v_mov_b32_e32 v3, v0
	v_mov_b32_e32 v4, v0
	v_mov_b32_e32 v5, v0
	v_mov_b32_e32 v6, v0
	v_mov_b32_e32 v7, v0
	v_mov_b32_e32 v8, v0
	v_mov_b32_e32 v9, v0
	v_mov_b32_e32 v10, v0
	v_mov_b32_e32 v11, v0
	v_mov_b32_e32 v12, v0
	v_mov_b32_e32 v13, v0
	s_lshl_b32 s30, s43, 12
	s_lshl_b32 s44, s48, 7
	v_mov_b64_e32 v[62:63], v[14:15]
	v_mov_b64_e32 v[46:47], v[14:15]
	v_mov_b64_e32 v[30:31], v[14:15]
	s_add_i32 s43, s30, 0xffffff80
	v_add_u32_e32 v153, s44, v171
	v_add_u32_e32 v155, s44, v172
	s_add_i32 s45, s46, 0x80
	s_mov_b32 s50, 2
	s_mov_b32 s51, 1
	s_mov_b32 s53, 0
	v_mov_b32_e32 v157, 0
	v_mov_b32_e32 v159, 0
	v_mov_b32_e32 v96, 0
	v_mov_b32_e32 v97, 0
	v_mov_b32_e32 v98, 0
	v_mov_b32_e32 v99, 0
	v_mov_b32_e32 v100, 0
	v_mov_b32_e32 v101, 0
	v_mov_b32_e32 v102, 0
	v_mov_b32_e32 v103, 0
	v_mov_b32_e32 v104, 0
	v_mov_b32_e32 v105, 0
	v_mov_b32_e32 v106, 0
	v_mov_b32_e32 v107, 0
	v_mov_b32_e32 v108, 0
	v_mov_b32_e32 v109, 0
	v_mov_b32_e32 v110, 0
	v_mov_b32_e32 v111, 0
	v_mov_b64_e32 v[60:61], v[12:13]
	v_mov_b64_e32 v[58:59], v[10:11]
	v_mov_b64_e32 v[56:57], v[8:9]
	v_mov_b64_e32 v[54:55], v[6:7]
	v_mov_b64_e32 v[52:53], v[4:5]
	v_mov_b64_e32 v[50:51], v[2:3]
	v_mov_b64_e32 v[48:49], v[0:1]
	v_mov_b64_e32 v[44:45], v[12:13]
	v_mov_b64_e32 v[42:43], v[10:11]
	v_mov_b64_e32 v[40:41], v[8:9]
	v_mov_b64_e32 v[38:39], v[6:7]
	v_mov_b64_e32 v[36:37], v[4:5]
	v_mov_b64_e32 v[34:35], v[2:3]
	v_mov_b64_e32 v[32:33], v[0:1]
	v_mov_b64_e32 v[28:29], v[12:13]
	v_mov_b64_e32 v[26:27], v[10:11]
	v_mov_b64_e32 v[24:25], v[8:9]
	v_mov_b64_e32 v[22:23], v[6:7]
	v_mov_b64_e32 v[20:21], v[4:5]
	v_mov_b64_e32 v[18:19], v[2:3]
	v_mov_b64_e32 v[16:17], v[0:1]
	s_mov_b32 s52, 0
	s_waitcnt vmcnt(0)
	s_mul_i32 s30, s53, 0x2400
	v_add_u32_e32 v242, s30, v173
	s_mul_i32 s30, s53, 0x4800
	v_add_u32_e32 v243, s30, v174
	v_readfirstlane_b32 s30, v191
	s_lshr_b32 s30, s30, 8
	s_cmp_eq_u32 s30, 0
	s_cbranch_scc1 .Latt_diff_p0
	s_setprio 1

.LBB0_116:
	ds_read_b128 v[112:115], v242 offset:0
	ds_read_b128 v[116:119], v242 offset:4608
	ds_read_b128 v[120:123], v242 offset:32
	ds_read_b128 v[124:127], v242 offset:4640
	ds_read_b128 v[202:205], v242 offset:64
	ds_read_b128 v[206:209], v242 offset:4672
	ds_read_b128 v[210:213], v242 offset:96
	ds_read_b128 v[214:217], v242 offset:4704
	s_waitcnt lgkmcnt(7)
	v_mfma_f32_32x32x16_bf16 v[64:79], v[112:115], v[130:133], v[96:111]
	s_waitcnt lgkmcnt(6)
	v_mfma_f32_32x32x16_bf16 v[80:95], v[116:119], v[130:133], v[96:111]
	s_waitcnt lgkmcnt(5)
	v_mfma_f32_32x32x16_bf16 v[64:79], v[120:123], v[134:137], v[64:79]
	s_waitcnt lgkmcnt(4)
	v_mfma_f32_32x32x16_bf16 v[80:95], v[124:127], v[134:137], v[80:95]
	s_waitcnt lgkmcnt(3)
	v_mfma_f32_32x32x16_bf16 v[64:79], v[202:205], v[138:141], v[64:79]
	s_waitcnt lgkmcnt(2)
	v_mfma_f32_32x32x16_bf16 v[80:95], v[206:209], v[138:141], v[80:95]
	s_waitcnt lgkmcnt(1)
	v_mfma_f32_32x32x16_bf16 v[64:79], v[210:213], v[142:145], v[64:79]
	s_waitcnt lgkmcnt(0)
	v_mfma_f32_32x32x16_bf16 v[80:95], v[214:217], v[142:145], v[80:95]
	ds_read_b128 v[112:115], v243 offset:27648
	ds_read_b128 v[116:119], v243 offset:32256
	ds_read_b128 v[120:123], v243 offset:36864
	ds_read_b128 v[124:127], v243 offset:41472
	ds_read_b128 v[202:205], v243 offset:27680
	ds_read_b128 v[206:209], v243 offset:32288
	ds_read_b128 v[210:213], v243 offset:36896
	ds_read_b128 v[214:217], v243 offset:41504
	s_cmp_eq_u32 s52, 0
	s_cselect_b32 s31, 0xff7fffff, 0
	s_nop 0
	v_max3_f32 v226, v64, v65, v66
	v_max3_f32 v227, v67, v68, v69
	v_max3_f32 v226, v226, v70, v71
	v_max3_f32 v227, v227, v72, v73
	v_max3_f32 v226, v226, v74, v75
	v_max3_f32 v227, v227, v76, v77
	v_max3_f32 v226, v226, v78, v79
	v_max3_f32 v228, v80, v81, v82
	v_max3_f32 v229, v83, v84, v85
	v_max3_f32 v228, v228, v86, v87
	v_max3_f32 v229, v229, v88, v89
	v_max3_f32 v228, v228, v90, v91
	v_max3_f32 v229, v229, v92, v93
	v_max3_f32 v228, v228, v94, v95
	v_max3_f32 v226, v226, v227, v228
	v_max_f32_e32 v226, v226, v229
	v_cmp_lt_f32_e32 vcc, s58, v226
	s_cmp_eq_u32 s52, 0
	s_cbranch_scc1 .Latt_diff_rare
	s_cbranch_vccnz .Latt_diff_rare

.Latt_diff_skip:
	s_and_b64 vcc, exec, s[46:47]
	s_cbranch_vccnz .Latt_diff_w0
	s_waitcnt vmcnt(3)
.Latt_diff_wd:
	s_add_i32 s30, s50, 1
	s_cmp_lg_u32 s50, 2
	s_cselect_b32 s46, s30, 0
	s_add_i32 s52, s52, 1
	s_add_i32 s43, s43, 64
	s_add_i32 s45, s45, 64
	s_mov_b32 s53, s51
	s_mov_b32 s51, s50
	s_mov_b32 s50, s46
	s_mul_i32 s30, s53, 0x2400
	v_add_u32_e32 v242, s30, v173
	s_mul_i32 s30, s53, 0x4800
	v_add_u32_e32 v243, s30, v174
	s_cmp_eq_u32 s21, s52
	s_waitcnt lgkmcnt(0)
	s_barrier
	s_cbranch_scc0 .LBB0_107
	s_branch .LBB0_88

.Latt_diff_rare:
	v_mov_b32_e32 v227, v226
	s_nop 1
	v_permlane32_swap_b32_e32 v226, v227
	v_max_f32_e32 v237, v226, v227
	v_max_f32_e32 v238, s31, v237
	v_max_f32_e32 v239, 0, v238
	v_add_f32_e32 v159, v159, v238
	v_exp_f32_e64 v240, -v239
	v_sub_f32_e32 v96, v96, v238
	v_mov_b32_e32 v97, v96
	v_mov_b32_e32 v98, v96
	v_mov_b32_e32 v99, v96
	v_mov_b32_e32 v100, v96
	v_mov_b32_e32 v101, v96
	v_mov_b32_e32 v102, v96
	v_mov_b32_e32 v103, v96
	v_mov_b32_e32 v104, v96
	v_mov_b32_e32 v105, v96
	v_mov_b32_e32 v106, v96
	v_mov_b32_e32 v107, v96
	v_mov_b32_e32 v108, v96
	v_mov_b32_e32 v109, v96
	v_mov_b32_e32 v110, v96
	v_mov_b32_e32 v111, v96
	v_sub_f32_e32 v64, v64, v238
	v_sub_f32_e32 v65, v65, v238
	v_sub_f32_e32 v66, v66, v238
	v_sub_f32_e32 v67, v67, v238
	v_sub_f32_e32 v68, v68, v238
	v_sub_f32_e32 v69, v69, v238
	v_sub_f32_e32 v70, v70, v238
	v_sub_f32_e32 v71, v71, v238
	v_sub_f32_e32 v72, v72, v238
	v_sub_f32_e32 v73, v73, v238
	v_sub_f32_e32 v74, v74, v238
	v_sub_f32_e32 v75, v75, v238
	v_sub_f32_e32 v76, v76, v238
	v_sub_f32_e32 v77, v77, v238
	v_sub_f32_e32 v78, v78, v238
	v_sub_f32_e32 v79, v79, v238
	v_sub_f32_e32 v80, v80, v238
	v_sub_f32_e32 v81, v81, v238
	v_sub_f32_e32 v82, v82, v238
	v_sub_f32_e32 v83, v83, v238
	v_sub_f32_e32 v84, v84, v238
	v_sub_f32_e32 v85, v85, v238
	v_sub_f32_e32 v86, v86, v238
	v_sub_f32_e32 v87, v87, v238
	v_sub_f32_e32 v88, v88, v238
	v_sub_f32_e32 v89, v89, v238
	v_sub_f32_e32 v90, v90, v238
	v_sub_f32_e32 v91, v91, v238
	v_sub_f32_e32 v92, v92, v238
	v_sub_f32_e32 v93, v93, v238
	v_sub_f32_e32 v94, v94, v238
	v_sub_f32_e32 v95, v95, v238
	v_mul_f32_e32 v157, v157, v240
	v_pk_mul_f32 v[0:1], v[0:1], v[240:241] op_sel_hi:[1,0]
	v_pk_mul_f32 v[2:3], v[2:3], v[240:241] op_sel_hi:[1,0]
	v_pk_mul_f32 v[4:5], v[4:5], v[240:241] op_sel_hi:[1,0]
	v_pk_mul_f32 v[6:7], v[6:7], v[240:241] op_sel_hi:[1,0]
	v_pk_mul_f32 v[8:9], v[8:9], v[240:241] op_sel_hi:[1,0]
	v_pk_mul_f32 v[10:11], v[10:11], v[240:241] op_sel_hi:[1,0]
	v_pk_mul_f32 v[12:13], v[12:13], v[240:241] op_sel_hi:[1,0]
	v_pk_mul_f32 v[14:15], v[14:15], v[240:241] op_sel_hi:[1,0]
	v_pk_mul_f32 v[48:49], v[48:49], v[240:241] op_sel_hi:[1,0]
	v_pk_mul_f32 v[50:51], v[50:51], v[240:241] op_sel_hi:[1,0]
	v_pk_mul_f32 v[52:53], v[52:53], v[240:241] op_sel_hi:[1,0]
	v_pk_mul_f32 v[54:55], v[54:55], v[240:241] op_sel_hi:[1,0]
	v_pk_mul_f32 v[56:57], v[56:57], v[240:241] op_sel_hi:[1,0]
	v_pk_mul_f32 v[58:59], v[58:59], v[240:241] op_sel_hi:[1,0]
	v_pk_mul_f32 v[60:61], v[60:61], v[240:241] op_sel_hi:[1,0]
	v_pk_mul_f32 v[62:63], v[62:63], v[240:241] op_sel_hi:[1,0]
	v_pk_mul_f32 v[32:33], v[32:33], v[240:241] op_sel_hi:[1,0]
	v_pk_mul_f32 v[34:35], v[34:35], v[240:241] op_sel_hi:[1,0]
	v_pk_mul_f32 v[36:37], v[36:37], v[240:241] op_sel_hi:[1,0]
	v_pk_mul_f32 v[38:39], v[38:39], v[240:241] op_sel_hi:[1,0]
	v_pk_mul_f32 v[40:41], v[40:41], v[240:241] op_sel_hi:[1,0]
	v_pk_mul_f32 v[42:43], v[42:43], v[240:241] op_sel_hi:[1,0]
	v_pk_mul_f32 v[44:45], v[44:45], v[240:241] op_sel_hi:[1,0]
	v_pk_mul_f32 v[46:47], v[46:47], v[240:241] op_sel_hi:[1,0]
	v_pk_mul_f32 v[16:17], v[16:17], v[240:241] op_sel_hi:[1,0]
	v_pk_mul_f32 v[18:19], v[18:19], v[240:241] op_sel_hi:[1,0]
	v_pk_mul_f32 v[20:21], v[20:21], v[240:241] op_sel_hi:[1,0]
	v_pk_mul_f32 v[22:23], v[22:23], v[240:241] op_sel_hi:[1,0]
	v_pk_mul_f32 v[24:25], v[24:25], v[240:241] op_sel_hi:[1,0]
	v_pk_mul_f32 v[26:27], v[26:27], v[240:241] op_sel_hi:[1,0]
	v_pk_mul_f32 v[28:29], v[28:29], v[240:241] op_sel_hi:[1,0]
	v_pk_mul_f32 v[30:31], v[30:31], v[240:241] op_sel_hi:[1,0]
	s_branch .Latt_diff_norescale

.LBB0_177:
	v_mov_b32_e32 v14, v0
	v_mov_b32_e32 v15, v0
	s_waitcnt vmcnt(0) lgkmcnt(0)
	s_barrier
	v_mov_b32_e32 v1, v0
	v_mov_b32_e32 v2, v0
	v_mov_b32_e32 v3, v0
	v_mov_b32_e32 v4, v0
	v_mov_b32_e32 v5, v0
	v_mov_b32_e32 v6, v0
	v_mov_b32_e32 v7, v0
	v_mov_b32_e32 v8, v0
	v_mov_b32_e32 v9, v0
	v_mov_b32_e32 v10, v0
	v_mov_b32_e32 v11, v0
	v_mov_b32_e32 v12, v0
	v_mov_b32_e32 v13, v0
	s_lshl_b32 s49, s49, 12
	v_mov_b64_e32 v[30:31], v[14:15]
	v_mov_b64_e32 v[46:47], v[14:15]
	v_mov_b64_e32 v[62:63], v[14:15]
	v_mad_u64_u32 v[222:223], s[30:31], s50, v238, v[190:191]
	v_mad_u64_u32 v[224:225], s[30:31], s50, v240, v[192:193]
	v_mad_u64_u32 v[226:227], s[30:31], s50, v242, v[194:195]
	v_mad_u64_u32 v[228:229], s[30:31], s50, v244, v[196:197]
	s_addk_i32 s49, 0xff80
	s_add_i32 s51, s60, 0x80
	s_mov_b32 s52, 2
	s_mov_b32 s53, 1
	s_mov_b32 s56, 0
	v_mov_b32_e32 v205, 0
	v_mov_b32_e32 v207, 0
	v_mov_b32_e32 v96, 0
	v_mov_b32_e32 v97, 0
	v_mov_b32_e32 v98, 0
	v_mov_b32_e32 v99, 0
	v_mov_b32_e32 v100, 0
	v_mov_b32_e32 v101, 0
	v_mov_b32_e32 v102, 0
	v_mov_b32_e32 v103, 0
	v_mov_b32_e32 v104, 0
	v_mov_b32_e32 v105, 0
	v_mov_b32_e32 v106, 0
	v_mov_b32_e32 v107, 0
	v_mov_b32_e32 v108, 0
	v_mov_b32_e32 v109, 0
	v_mov_b32_e32 v110, 0
	v_mov_b32_e32 v111, 0
	v_mov_b64_e32 v[28:29], v[12:13]
	v_mov_b64_e32 v[26:27], v[10:11]
	v_mov_b64_e32 v[24:25], v[8:9]
	v_mov_b64_e32 v[22:23], v[6:7]
	v_mov_b64_e32 v[20:21], v[4:5]
	v_mov_b64_e32 v[18:19], v[2:3]
	v_mov_b64_e32 v[16:17], v[0:1]
	v_mov_b64_e32 v[44:45], v[12:13]
	v_mov_b64_e32 v[42:43], v[10:11]
	v_mov_b64_e32 v[40:41], v[8:9]
	v_mov_b64_e32 v[38:39], v[6:7]
	v_mov_b64_e32 v[36:37], v[4:5]
	v_mov_b64_e32 v[34:35], v[2:3]
	v_mov_b64_e32 v[32:33], v[0:1]
	v_mov_b64_e32 v[60:61], v[12:13]
	v_mov_b64_e32 v[58:59], v[10:11]
	v_mov_b64_e32 v[56:57], v[8:9]
	v_mov_b64_e32 v[54:55], v[6:7]
	v_mov_b64_e32 v[52:53], v[4:5]
	v_mov_b64_e32 v[50:51], v[2:3]
	v_mov_b64_e32 v[48:49], v[0:1]
	s_mov_b32 s55, 0
	s_waitcnt vmcnt(0)
	s_mul_i32 s30, s56, 0x6400
	v_add_u32_e32 v209, s30, v246
	s_mul_i32 s30, s56, 0x4800
	v_add_u32_e32 v219, s30, v247
	v_readfirstlane_b32 s30, v191
	s_lshr_b32 s30, s30, 8
	s_cmp_eq_u32 s30, 0
	s_cbranch_scc1 .Latt_mla_p0
	s_setprio 1

.LBB0_191:
	ds_read_b128 v[112:115], v209 offset:0
	ds_read_b128 v[116:119], v209 offset:12800
	ds_read_b128 v[120:123], v209 offset:32
	ds_read_b128 v[124:127], v209 offset:12832
	ds_read_b128 v[250:253], v209 offset:64
	s_waitcnt lgkmcnt(4)
	v_mfma_f32_32x32x16_bf16 v[64:79], v[112:115], v[130:133], v[96:111]
	ds_read_b128 v[112:115], v209 offset:12864
	s_waitcnt lgkmcnt(4)
	v_mfma_f32_32x32x16_bf16 v[80:95], v[116:119], v[130:133], v[96:111]
	ds_read_b128 v[116:119], v209 offset:96
	s_waitcnt lgkmcnt(4)
	v_mfma_f32_32x32x16_bf16 v[64:79], v[120:123], v[134:137], v[64:79]
	ds_read_b128 v[120:123], v209 offset:12896
	s_waitcnt lgkmcnt(4)
	v_mfma_f32_32x32x16_bf16 v[80:95], v[124:127], v[134:137], v[80:95]
	ds_read_b128 v[124:127], v209 offset:128
	s_waitcnt lgkmcnt(4)
	v_mfma_f32_32x32x16_bf16 v[64:79], v[250:253], v[138:141], v[64:79]
	ds_read_b128 v[250:253], v209 offset:12928
	s_waitcnt lgkmcnt(4)
	v_mfma_f32_32x32x16_bf16 v[80:95], v[112:115], v[138:141], v[80:95]
	ds_read_b128 v[112:115], v209 offset:160
	s_waitcnt lgkmcnt(4)
	v_mfma_f32_32x32x16_bf16 v[64:79], v[116:119], v[142:145], v[64:79]
	ds_read_b128 v[116:119], v209 offset:12960
	s_waitcnt lgkmcnt(4)
	v_mfma_f32_32x32x16_bf16 v[80:95], v[120:123], v[142:145], v[80:95]
	ds_read_b128 v[120:123], v209 offset:192
	s_waitcnt lgkmcnt(4)
	v_mfma_f32_32x32x16_bf16 v[64:79], v[124:127], v[146:149], v[64:79]
	ds_read_b128 v[124:127], v209 offset:12992
	s_waitcnt lgkmcnt(4)
	v_mfma_f32_32x32x16_bf16 v[80:95], v[250:253], v[146:149], v[80:95]
	ds_read_b128 v[250:253], v209 offset:224
	s_waitcnt lgkmcnt(4)
	v_mfma_f32_32x32x16_bf16 v[64:79], v[112:115], v[150:153], v[64:79]
	ds_read_b128 v[112:115], v209 offset:13024
	s_waitcnt lgkmcnt(4)
	v_mfma_f32_32x32x16_bf16 v[80:95], v[116:119], v[150:153], v[80:95]
	ds_read_b128 v[116:119], v209 offset:256
	s_waitcnt lgkmcnt(4)
	v_mfma_f32_32x32x16_bf16 v[64:79], v[120:123], v[154:157], v[64:79]
	ds_read_b128 v[120:123], v209 offset:13056
	s_waitcnt lgkmcnt(4)
	v_mfma_f32_32x32x16_bf16 v[80:95], v[124:127], v[154:157], v[80:95]
	ds_read_b128 v[124:127], v209 offset:288
	s_waitcnt lgkmcnt(4)
	v_mfma_f32_32x32x16_bf16 v[64:79], v[250:253], v[158:161], v[64:79]
	ds_read_b128 v[250:253], v209 offset:13088
	s_waitcnt lgkmcnt(4)
	v_mfma_f32_32x32x16_bf16 v[80:95], v[112:115], v[158:161], v[80:95]
	ds_read_b128 v[112:115], v209 offset:320
	s_waitcnt lgkmcnt(4)
	v_mfma_f32_32x32x16_bf16 v[64:79], v[116:119], v[162:165], v[64:79]
	ds_read_b128 v[116:119], v209 offset:13120
	s_waitcnt lgkmcnt(4)
	v_mfma_f32_32x32x16_bf16 v[80:95], v[120:123], v[162:165], v[80:95]
	ds_read_b128 v[120:123], v209 offset:352
	s_waitcnt lgkmcnt(4)
	v_mfma_f32_32x32x16_bf16 v[64:79], v[124:127], v[166:169], v[64:79]
	ds_read_b128 v[124:127], v209 offset:13152
	s_waitcnt lgkmcnt(4)
	v_mfma_f32_32x32x16_bf16 v[80:95], v[250:253], v[166:169], v[80:95]
	s_waitcnt lgkmcnt(3)
	v_mfma_f32_32x32x16_bf16 v[64:79], v[112:115], v[170:173], v[64:79]
	s_waitcnt lgkmcnt(2)
	v_mfma_f32_32x32x16_bf16 v[80:95], v[116:119], v[170:173], v[80:95]
	s_waitcnt lgkmcnt(1)
	v_mfma_f32_32x32x16_bf16 v[64:79], v[120:123], v[174:177], v[64:79]
	s_waitcnt lgkmcnt(0)
	v_mfma_f32_32x32x16_bf16 v[80:95], v[124:127], v[174:177], v[80:95]
	ds_read_b128 v[112:115], v219 offset:0
	ds_read_b128 v[116:119], v219 offset:4608
	ds_read_b128 v[120:123], v219 offset:9216
	s_cmp_eq_u32 s55, 0
	s_cselect_b32 s31, 0xff7fffff, 0
	s_nop 5
	v_max3_f32 v209, v64, v65, v66
	v_max3_f32 v211, v67, v68, v69
	v_max3_f32 v209, v209, v70, v71
	v_max3_f32 v211, v211, v72, v73
	v_max3_f32 v209, v209, v74, v75
	v_max3_f32 v211, v211, v76, v77
	v_max3_f32 v209, v209, v78, v79
	v_max3_f32 v213, v80, v81, v82
	v_max3_f32 v215, v83, v84, v85
	v_max3_f32 v213, v213, v86, v87
	v_max3_f32 v215, v215, v88, v89
	v_max3_f32 v213, v213, v90, v91
	v_max3_f32 v215, v215, v92, v93
	v_max3_f32 v213, v213, v94, v95
	v_max3_f32 v209, v209, v211, v213
	v_max_f32_e32 v209, v209, v215
	v_cmp_lt_f32_e32 vcc, s58, v209
	s_cmp_eq_u32 s55, 0
	s_cbranch_scc1 .Latt_mla_rare
	s_cbranch_vccnz .Latt_mla_rare

.Latt_mla_skip:
	s_and_b64 vcc, exec, s[60:61]
	s_cbranch_vccnz .Latt_mla_w0
	s_waitcnt vmcnt(5)
.Latt_mla_wd:
	s_add_i32 s30, s52, 1
	s_cmp_lg_u32 s52, 2
	s_cselect_b32 s57, s30, 0
	s_add_i32 s55, s55, 1
	s_add_i32 s49, s49, 64
	s_add_i32 s51, s51, 64
	s_mov_b32 s56, s53
	s_mov_b32 s53, s52
	s_mov_b32 s52, s57
	s_mul_i32 s30, s56, 0x6400
	v_add_u32_e32 v209, s30, v246
	s_mul_i32 s30, s56, 0x4800
	v_add_u32_e32 v219, s30, v247
	s_cmp_eq_u32 s20, s55
	s_waitcnt lgkmcnt(0)
	s_barrier
	s_cbranch_scc0 .LBB0_178
	s_branch .LBB0_153

.Latt_mla_rare:
	v_mov_b32_e32 v211, v209
	s_nop 1
	v_permlane32_swap_b32_e32 v209, v211
	v_max_f32_e32 v217, v209, v211
	v_max_f32_e32 v211, s31, v217
	v_max_f32_e32 v213, 0, v211
	v_add_f32_e32 v207, v207, v211
	v_exp_f32_e64 v250, -v213
	v_sub_f32_e32 v96, v96, v211
	v_mov_b32_e32 v97, v96
	v_mov_b32_e32 v98, v96
	v_mov_b32_e32 v99, v96
	v_mov_b32_e32 v100, v96
	v_mov_b32_e32 v101, v96
	v_mov_b32_e32 v102, v96
	v_mov_b32_e32 v103, v96
	v_mov_b32_e32 v104, v96
	v_mov_b32_e32 v105, v96
	v_mov_b32_e32 v106, v96
	v_mov_b32_e32 v107, v96
	v_mov_b32_e32 v108, v96
	v_mov_b32_e32 v109, v96
	v_mov_b32_e32 v110, v96
	v_mov_b32_e32 v111, v96
	v_sub_f32_e32 v64, v64, v211
	v_sub_f32_e32 v65, v65, v211
	v_sub_f32_e32 v66, v66, v211
	v_sub_f32_e32 v67, v67, v211
	v_sub_f32_e32 v68, v68, v211
	v_sub_f32_e32 v69, v69, v211
	v_sub_f32_e32 v70, v70, v211
	v_sub_f32_e32 v71, v71, v211
	v_sub_f32_e32 v72, v72, v211
	v_sub_f32_e32 v73, v73, v211
	v_sub_f32_e32 v74, v74, v211
	v_sub_f32_e32 v75, v75, v211
	v_sub_f32_e32 v76, v76, v211
	v_sub_f32_e32 v77, v77, v211
	v_sub_f32_e32 v78, v78, v211
	v_sub_f32_e32 v79, v79, v211
	v_sub_f32_e32 v80, v80, v211
	v_sub_f32_e32 v81, v81, v211
	v_sub_f32_e32 v82, v82, v211
	v_sub_f32_e32 v83, v83, v211
	v_sub_f32_e32 v84, v84, v211
	v_sub_f32_e32 v85, v85, v211
	v_sub_f32_e32 v86, v86, v211
	v_sub_f32_e32 v87, v87, v211
	v_sub_f32_e32 v88, v88, v211
	v_sub_f32_e32 v89, v89, v211
	v_sub_f32_e32 v90, v90, v211
	v_sub_f32_e32 v91, v91, v211
	v_sub_f32_e32 v92, v92, v211
	v_sub_f32_e32 v93, v93, v211
	v_sub_f32_e32 v94, v94, v211
	v_sub_f32_e32 v95, v95, v211
	v_mul_f32_e32 v205, v205, v250
	v_pk_mul_f32 v[48:49], v[48:49], v[250:251] op_sel_hi:[1,0]
	v_pk_mul_f32 v[50:51], v[50:51], v[250:251] op_sel_hi:[1,0]
	v_pk_mul_f32 v[52:53], v[52:53], v[250:251] op_sel_hi:[1,0]
	v_pk_mul_f32 v[54:55], v[54:55], v[250:251] op_sel_hi:[1,0]
	v_pk_mul_f32 v[56:57], v[56:57], v[250:251] op_sel_hi:[1,0]
	v_pk_mul_f32 v[58:59], v[58:59], v[250:251] op_sel_hi:[1,0]
	v_pk_mul_f32 v[60:61], v[60:61], v[250:251] op_sel_hi:[1,0]
	v_pk_mul_f32 v[62:63], v[62:63], v[250:251] op_sel_hi:[1,0]
	v_pk_mul_f32 v[32:33], v[32:33], v[250:251] op_sel_hi:[1,0]
	v_pk_mul_f32 v[34:35], v[34:35], v[250:251] op_sel_hi:[1,0]
	v_pk_mul_f32 v[36:37], v[36:37], v[250:251] op_sel_hi:[1,0]
	v_pk_mul_f32 v[38:39], v[38:39], v[250:251] op_sel_hi:[1,0]
	v_pk_mul_f32 v[40:41], v[40:41], v[250:251] op_sel_hi:[1,0]
	v_pk_mul_f32 v[42:43], v[42:43], v[250:251] op_sel_hi:[1,0]
	v_pk_mul_f32 v[44:45], v[44:45], v[250:251] op_sel_hi:[1,0]
	v_pk_mul_f32 v[46:47], v[46:47], v[250:251] op_sel_hi:[1,0]
	v_pk_mul_f32 v[16:17], v[16:17], v[250:251] op_sel_hi:[1,0]
	v_pk_mul_f32 v[18:19], v[18:19], v[250:251] op_sel_hi:[1,0]
	v_pk_mul_f32 v[20:21], v[20:21], v[250:251] op_sel_hi:[1,0]
	v_pk_mul_f32 v[22:23], v[22:23], v[250:251] op_sel_hi:[1,0]
	v_pk_mul_f32 v[24:25], v[24:25], v[250:251] op_sel_hi:[1,0]
	v_pk_mul_f32 v[26:27], v[26:27], v[250:251] op_sel_hi:[1,0]
	v_pk_mul_f32 v[28:29], v[28:29], v[250:251] op_sel_hi:[1,0]
	v_pk_mul_f32 v[30:31], v[30:31], v[250:251] op_sel_hi:[1,0]
	v_pk_mul_f32 v[0:1], v[0:1], v[250:251] op_sel_hi:[1,0]
	v_pk_mul_f32 v[2:3], v[2:3], v[250:251] op_sel_hi:[1,0]
	v_pk_mul_f32 v[4:5], v[4:5], v[250:251] op_sel_hi:[1,0]
	v_pk_mul_f32 v[6:7], v[6:7], v[250:251] op_sel_hi:[1,0]
	v_pk_mul_f32 v[8:9], v[8:9], v[250:251] op_sel_hi:[1,0]
	v_pk_mul_f32 v[10:11], v[10:11], v[250:251] op_sel_hi:[1,0]
	v_pk_mul_f32 v[12:13], v[12:13], v[250:251] op_sel_hi:[1,0]
	v_pk_mul_f32 v[14:15], v[14:15], v[250:251] op_sel_hi:[1,0]
	s_branch .Latt_mla_norescale
